# v46 + SwiGLU epilogue store addresses as 32-bit offsets (v_mad_u32_u24 + saddr-form store) instead of 64-bit mad + add
# baseline (speedup 1.0000x reference)
; __device__ __forceinline__ unsigned pk2(float lo, float hi) { const f32x2 v = {lo, hi}; return __builtin_bit_cast(unsigned, __builtin_convertvector(v, bf16x2_t)); }
;     __device__ __forceinline__ void operator()(const f32x4 (&acc)[2][2][4][2], const Unit& u, int wr, int wc, int fr, int fq) const {
;     ...
;         for (int ai = 0; ai < 2; ++ai)
; #pragma unroll
;             for (int m = 0; m < 4; ++m) {
;                 const float rs = rs8[ai][m], nrs = -1.44269504089f * rs;
;                 u32x4 w;
; #pragma unroll
;                 for (int n = 0; n < 2; ++n) { const f32x4 gq = acc[ai][0][m][n], uq = acc[ai][1][m][n];
; #pragma unroll
;                     for (int h = 0; h < 2; ++h) { const f32x2 gv = (f32x2){gq[2 * h], gq[2 * h + 1]}, uv = (f32x2){uq[2 * h], uq[2 * h + 1]};
;                         const f32x2 ea = gv * nrs; f32x2 e; e.x = __builtin_amdgcn_exp2f(ea.x); e.y = __builtin_amdgcn_exp2f(ea.y);
;                         const f32x2 d = e + 1.0f; f32x2 rc; rc.x = __builtin_amdgcn_rcpf(d.x); rc.y = __builtin_amdgcn_rcpf(d.y);
;                         const f32x2 o = (gv * uv) * (rc * (rs * rs));
;                         w[2 * n + h] = pk2(o.x, o.y); } }
;                 *(u32x4*)(O + (size_t)(row0 + ai * HALF + m * 16) * ldc + col0) = w; }
.Lmy_sw_join:
	v_lshl_or_b32 v162, s53, 7, v160
	v_mul_f32_e32 v164, 0xbfb8aa3b, v147
	v_pk_mul_f32 v[166:167], v[130:131], v[164:165] op_sel_hi:[1,0]
	v_pk_mul_f32 v[126:127], v[130:131], v[126:127]
	v_exp_f32_e32 v166, v166
	v_exp_f32_e32 v167, v167
	v_pk_mul_f32 v[130:131], v[132:133], v[164:165] op_sel_hi:[1,0]
	v_mul_f32_e32 v168, v147, v147
	v_exp_f32_e32 v130, v130
	v_exp_f32_e32 v131, v131
	v_pk_add_f32 v[166:167], v[166:167], 1.0 op_sel_hi:[1,0]
	v_pk_mul_f32 v[128:129], v[132:133], v[128:129]
	v_rcp_f32_e32 v166, v166
	v_rcp_f32_e32 v167, v167
	v_pk_add_f32 v[130:131], v[130:131], 1.0 op_sel_hi:[1,0]
	v_pk_mul_f32 v[118:119], v[122:123], v[118:119]
	v_rcp_f32_e32 v130, v130
	v_rcp_f32_e32 v131, v131
	v_pk_mul_f32 v[132:133], v[168:169], v[166:167] op_sel_hi:[0,1]
	v_pk_mul_f32 v[126:127], v[126:127], v[132:133]
	v_pk_mul_f32 v[132:133], v[122:123], v[164:165] op_sel_hi:[1,0]
	v_pk_mul_f32 v[130:131], v[168:169], v[130:131] op_sel_hi:[0,1]
	v_exp_f32_e32 v132, v132
	v_exp_f32_e32 v133, v133
	v_pk_mul_f32 v[128:129], v[128:129], v[130:131]
	v_pk_mul_f32 v[130:131], v[124:125], v[164:165] op_sel_hi:[1,0]
	v_cvt_pk_bf16_f32 v126, v126, v127
	v_exp_f32_e32 v130, v130
	v_exp_f32_e32 v131, v131
	v_cvt_pk_bf16_f32 v127, v128, v129
	v_pk_add_f32 v[128:129], v[132:133], 1.0 op_sel_hi:[1,0]
	v_pk_mul_f32 v[120:121], v[124:125], v[120:121]
	v_rcp_f32_e32 v128, v128
	v_rcp_f32_e32 v129, v129
	v_pk_add_f32 v[122:123], v[130:131], 1.0 op_sel_hi:[1,0]
	v_ashrrev_i32_e32 v163, 31, v162
	v_rcp_f32_e32 v122, v122
	v_rcp_f32_e32 v123, v123
	v_pk_mul_f32 v[124:125], v[168:169], v[128:129] op_sel_hi:[0,1]
	v_pk_mul_f32 v[118:119], v[118:119], v[124:125]
	v_mul_f32_e32 v124, 0xbfb8aa3b, v149
	v_cvt_pk_bf16_f32 v128, v118, v119
	v_pk_mul_f32 v[118:119], v[168:169], v[122:123] op_sel_hi:[0,1]
	v_pk_mul_f32 v[130:131], v[114:115], v[124:125] op_sel_hi:[1,0]
	v_pk_mul_f32 v[118:119], v[120:121], v[118:119]
	v_exp_f32_e32 v130, v130
	v_exp_f32_e32 v131, v131
	v_cvt_pk_bf16_f32 v129, v118, v119
	v_pk_mul_f32 v[110:111], v[114:115], v[110:111]
	v_pk_mul_f32 v[114:115], v[116:117], v[124:125] op_sel_hi:[1,0]
	v_lshlrev_b64 v[120:121], 1, v[162:163]
	v_exp_f32_e32 v114, v114
	v_exp_f32_e32 v115, v115
	v_mad_u32_u24 v122, v156, s1, v120
	global_store_dwordx4 v122, v[126:129], s[12:13]
	v_mul_f32_e32 v122, v149, v149
	v_pk_add_f32 v[114:115], v[114:115], 1.0 op_sel_hi:[1,0]
	v_pk_add_f32 v[126:127], v[130:131], 1.0 op_sel_hi:[1,0]
	v_rcp_f32_e32 v114, v114
	v_rcp_f32_e32 v126, v126
	v_rcp_f32_e32 v127, v127
	v_rcp_f32_e32 v115, v115
	v_pk_mul_f32 v[112:113], v[116:117], v[112:113]
	v_pk_mul_f32 v[102:103], v[106:107], v[102:103]
	v_pk_mul_f32 v[116:117], v[122:123], v[126:127] op_sel_hi:[0,1]
	v_pk_mul_f32 v[110:111], v[110:111], v[116:117]
	v_pk_mul_f32 v[116:117], v[106:107], v[124:125] op_sel_hi:[1,0]
	v_pk_mul_f32 v[114:115], v[122:123], v[114:115] op_sel_hi:[0,1]
	v_exp_f32_e32 v116, v116
	v_exp_f32_e32 v117, v117
	v_pk_mul_f32 v[112:113], v[112:113], v[114:115]
	v_pk_mul_f32 v[114:115], v[108:109], v[124:125] op_sel_hi:[1,0]
	v_cvt_pk_bf16_f32 v110, v110, v111
	v_exp_f32_e32 v114, v114
	v_exp_f32_e32 v115, v115
	v_cvt_pk_bf16_f32 v111, v112, v113
	v_pk_add_f32 v[112:113], v[116:117], 1.0 op_sel_hi:[1,0]
	v_pk_mul_f32 v[104:105], v[108:109], v[104:105]
	v_rcp_f32_e32 v112, v112
	v_rcp_f32_e32 v113, v113
	v_pk_add_f32 v[106:107], v[114:115], 1.0 op_sel_hi:[1,0]
	v_pk_mul_f32 v[94:95], v[98:99], v[94:95]
	v_rcp_f32_e32 v106, v106
	v_rcp_f32_e32 v107, v107
	v_pk_mul_f32 v[108:109], v[122:123], v[112:113] op_sel_hi:[0,1]
	v_pk_mul_f32 v[102:103], v[102:103], v[108:109]
	v_pk_mul_f32 v[96:97], v[100:101], v[96:97]
	v_cvt_pk_bf16_f32 v112, v102, v103
	v_pk_mul_f32 v[102:103], v[122:123], v[106:107] op_sel_hi:[0,1]
	v_pk_mul_f32 v[102:103], v[104:105], v[102:103]
	v_mul_f32_e32 v104, 0xbfb8aa3b, v151
	v_pk_mul_f32 v[106:107], v[98:99], v[104:105] op_sel_hi:[1,0]
	v_pk_mul_f32 v[98:99], v[100:101], v[104:105] op_sel_hi:[1,0]
	v_exp_f32_e32 v106, v106
	v_exp_f32_e32 v107, v107
	v_exp_f32_e32 v98, v98
	v_exp_f32_e32 v99, v99
	v_cvt_pk_bf16_f32 v113, v102, v103
	v_pk_add_f32 v[106:107], v[106:107], 1.0 op_sel_hi:[1,0]
	v_mad_u32_u24 v102, v154, s1, v120
	v_rcp_f32_e32 v106, v106
	v_rcp_f32_e32 v107, v107
	v_pk_add_f32 v[98:99], v[98:99], 1.0 op_sel_hi:[1,0]
	v_rcp_f32_e32 v98, v98
	v_rcp_f32_e32 v99, v99
	global_store_dwordx4 v102, v[110:113], s[12:13]
	v_mul_f32_e32 v102, v151, v151
	v_pk_mul_f32 v[100:101], v[102:103], v[106:107] op_sel_hi:[0,1]
	v_pk_mul_f32 v[94:95], v[94:95], v[100:101]
	v_pk_mul_f32 v[100:101], v[90:91], v[104:105] op_sel_hi:[1,0]
	v_pk_mul_f32 v[98:99], v[102:103], v[98:99] op_sel_hi:[0,1]
	v_exp_f32_e32 v100, v100
	v_exp_f32_e32 v101, v101
	v_pk_mul_f32 v[96:97], v[96:97], v[98:99]
	v_pk_mul_f32 v[98:99], v[92:93], v[104:105] op_sel_hi:[1,0]
	v_cvt_pk_bf16_f32 v94, v94, v95
	v_exp_f32_e32 v98, v98
	v_exp_f32_e32 v99, v99
	v_cvt_pk_bf16_f32 v95, v96, v97
	v_pk_add_f32 v[96:97], v[100:101], 1.0 op_sel_hi:[1,0]
	v_pk_mul_f32 v[86:87], v[90:91], v[86:87]
	v_rcp_f32_e32 v96, v96
	v_rcp_f32_e32 v97, v97
	v_pk_add_f32 v[90:91], v[98:99], 1.0 op_sel_hi:[1,0]
	v_pk_mul_f32 v[88:89], v[92:93], v[88:89]
	v_rcp_f32_e32 v90, v90
	v_rcp_f32_e32 v91, v91
	v_pk_mul_f32 v[92:93], v[102:103], v[96:97] op_sel_hi:[0,1]
	v_pk_mul_f32 v[86:87], v[86:87], v[92:93]
	v_pk_mul_f32 v[78:79], v[82:83], v[78:79]
	v_cvt_pk_bf16_f32 v96, v86, v87
	v_pk_mul_f32 v[86:87], v[102:103], v[90:91] op_sel_hi:[0,1]
	v_pk_mul_f32 v[86:87], v[88:89], v[86:87]
	v_mul_f32_e32 v88, 0xbfb8aa3b, v153
	v_pk_mul_f32 v[90:91], v[82:83], v[88:89] op_sel_hi:[1,0]
; __device__ __forceinline__ unsigned pk2(float lo, float hi) { const f32x2 v = {lo, hi}; return __builtin_bit_cast(unsigned, __builtin_convertvector(v, bf16x2_t)); }
;     __device__ __forceinline__ void operator()(const f32x4 (&acc)[2][2][4][2], const Unit& u, int wr, int wc, int fr, int fq) const {
;     ...
;         for (int ai = 0; ai < 2; ++ai)
; #pragma unroll
;             for (int m = 0; m < 4; ++m) {
;                 const float rs = rs8[ai][m], nrs = -1.44269504089f * rs;
;                 u32x4 w;
; #pragma unroll
;                 for (int n = 0; n < 2; ++n) { const f32x4 gq = acc[ai][0][m][n], uq = acc[ai][1][m][n];
; #pragma unroll
;                     for (int h = 0; h < 2; ++h) { const f32x2 gv = (f32x2){gq[2 * h], gq[2 * h + 1]}, uv = (f32x2){uq[2 * h], uq[2 * h + 1]};
;                         const f32x2 ea = gv * nrs; f32x2 e; e.x = __builtin_amdgcn_exp2f(ea.x); e.y = __builtin_amdgcn_exp2f(ea.y);
;                         const f32x2 d = e + 1.0f; f32x2 rc; rc.x = __builtin_amdgcn_rcpf(d.x); rc.y = __builtin_amdgcn_rcpf(d.y);
;                         const f32x2 o = (gv * uv) * (rc * (rs * rs));
;                         w[2 * n + h] = pk2(o.x, o.y); } }
;                 *(u32x4*)(O + (size_t)(row0 + ai * HALF + m * 16) * ldc + col0) = w; }
	v_pk_mul_f32 v[82:83], v[84:85], v[88:89] op_sel_hi:[1,0]
	v_exp_f32_e32 v90, v90
	v_exp_f32_e32 v91, v91
	v_exp_f32_e32 v82, v82
	v_exp_f32_e32 v83, v83
	v_cvt_pk_bf16_f32 v97, v86, v87
	v_pk_add_f32 v[90:91], v[90:91], 1.0 op_sel_hi:[1,0]
	v_mad_u32_u24 v86, v152, s1, v120
	v_rcp_f32_e32 v90, v90
	v_rcp_f32_e32 v91, v91
	v_pk_add_f32 v[82:83], v[82:83], 1.0 op_sel_hi:[1,0]
	v_rcp_f32_e32 v82, v82
	v_rcp_f32_e32 v83, v83
	global_store_dwordx4 v86, v[94:97], s[12:13]
	v_mul_f32_e32 v86, v153, v153
	v_pk_mul_f32 v[80:81], v[84:85], v[80:81]
	v_pk_mul_f32 v[84:85], v[86:87], v[90:91] op_sel_hi:[0,1]
	v_pk_mul_f32 v[78:79], v[78:79], v[84:85]
	v_pk_mul_f32 v[84:85], v[74:75], v[88:89] op_sel_hi:[1,0]
	v_pk_mul_f32 v[82:83], v[86:87], v[82:83] op_sel_hi:[0,1]
	v_exp_f32_e32 v84, v84
	v_exp_f32_e32 v85, v85
	v_pk_mul_f32 v[80:81], v[80:81], v[82:83]
	v_pk_mul_f32 v[82:83], v[76:77], v[88:89] op_sel_hi:[1,0]
	v_cvt_pk_bf16_f32 v78, v78, v79
	v_exp_f32_e32 v82, v82
	v_exp_f32_e32 v83, v83
	v_cvt_pk_bf16_f32 v79, v80, v81
	v_pk_add_f32 v[80:81], v[84:85], 1.0 op_sel_hi:[1,0]
	v_pk_mul_f32 v[70:71], v[74:75], v[70:71]
	v_rcp_f32_e32 v80, v80
	v_rcp_f32_e32 v81, v81
	v_pk_add_f32 v[74:75], v[82:83], 1.0 op_sel_hi:[1,0]
	v_pk_mul_f32 v[72:73], v[76:77], v[72:73]
	v_rcp_f32_e32 v74, v74
	v_rcp_f32_e32 v75, v75
	v_pk_mul_f32 v[76:77], v[86:87], v[80:81] op_sel_hi:[0,1]
	v_pk_mul_f32 v[70:71], v[70:71], v[76:77]
	v_pk_mul_f32 v[62:63], v[66:67], v[62:63]
	v_cvt_pk_bf16_f32 v80, v70, v71
	v_pk_mul_f32 v[70:71], v[86:87], v[74:75] op_sel_hi:[0,1]
	v_pk_mul_f32 v[70:71], v[72:73], v[70:71]
	v_mul_f32_e32 v72, 0xbfb8aa3b, v155
	v_pk_mul_f32 v[74:75], v[66:67], v[72:73] op_sel_hi:[1,0]
	v_pk_mul_f32 v[66:67], v[68:69], v[72:73] op_sel_hi:[1,0]
	v_exp_f32_e32 v74, v74
	v_exp_f32_e32 v75, v75
	v_exp_f32_e32 v66, v66
	v_exp_f32_e32 v67, v67
	v_cvt_pk_bf16_f32 v81, v70, v71
	v_pk_add_f32 v[74:75], v[74:75], 1.0 op_sel_hi:[1,0]
	v_mad_u32_u24 v70, v150, s1, v120
	v_rcp_f32_e32 v74, v74
	v_rcp_f32_e32 v75, v75
	v_pk_add_f32 v[66:67], v[66:67], 1.0 op_sel_hi:[1,0]
	v_rcp_f32_e32 v66, v66
	v_rcp_f32_e32 v67, v67
	global_store_dwordx4 v70, v[78:81], s[12:13]
	v_mul_f32_e32 v70, v155, v155
	v_pk_mul_f32 v[64:65], v[68:69], v[64:65]
	v_pk_mul_f32 v[68:69], v[70:71], v[74:75] op_sel_hi:[0,1]
	v_pk_mul_f32 v[62:63], v[62:63], v[68:69]
	v_pk_mul_f32 v[68:69], v[58:59], v[72:73] op_sel_hi:[1,0]
	v_pk_mul_f32 v[66:67], v[70:71], v[66:67] op_sel_hi:[0,1]
	v_exp_f32_e32 v68, v68
	v_exp_f32_e32 v69, v69
	v_pk_mul_f32 v[64:65], v[64:65], v[66:67]
	v_pk_mul_f32 v[66:67], v[60:61], v[72:73] op_sel_hi:[1,0]
	v_cvt_pk_bf16_f32 v62, v62, v63
	v_exp_f32_e32 v66, v66
	v_exp_f32_e32 v67, v67
	v_cvt_pk_bf16_f32 v63, v64, v65
	v_pk_add_f32 v[64:65], v[68:69], 1.0 op_sel_hi:[1,0]
	v_pk_mul_f32 v[54:55], v[58:59], v[54:55]
	v_rcp_f32_e32 v64, v64
	v_rcp_f32_e32 v65, v65
	v_pk_add_f32 v[58:59], v[66:67], 1.0 op_sel_hi:[1,0]
	v_pk_mul_f32 v[56:57], v[60:61], v[56:57]
	v_rcp_f32_e32 v58, v58
	v_rcp_f32_e32 v59, v59
	v_pk_mul_f32 v[60:61], v[70:71], v[64:65] op_sel_hi:[0,1]
	v_pk_mul_f32 v[54:55], v[54:55], v[60:61]
	v_pk_mul_f32 v[46:47], v[50:51], v[46:47]
	v_cvt_pk_bf16_f32 v64, v54, v55
	v_pk_mul_f32 v[54:55], v[70:71], v[58:59] op_sel_hi:[0,1]
	v_pk_mul_f32 v[54:55], v[56:57], v[54:55]
	v_mul_f32_e32 v56, 0xbfb8aa3b, v157
	v_pk_mul_f32 v[58:59], v[50:51], v[56:57] op_sel_hi:[1,0]
	v_pk_mul_f32 v[50:51], v[52:53], v[56:57] op_sel_hi:[1,0]
	v_exp_f32_e32 v58, v58
	v_exp_f32_e32 v59, v59
	v_exp_f32_e32 v50, v50
	v_exp_f32_e32 v51, v51
	v_cvt_pk_bf16_f32 v65, v54, v55
	v_pk_add_f32 v[58:59], v[58:59], 1.0 op_sel_hi:[1,0]
	v_mad_u32_u24 v54, v148, s1, v120
	v_rcp_f32_e32 v58, v58
	v_rcp_f32_e32 v59, v59
	v_pk_add_f32 v[50:51], v[50:51], 1.0 op_sel_hi:[1,0]
	v_rcp_f32_e32 v50, v50
	v_rcp_f32_e32 v51, v51
	global_store_dwordx4 v54, v[62:65], s[12:13]
	v_mul_f32_e32 v54, v157, v157
	v_pk_mul_f32 v[48:49], v[52:53], v[48:49]
	v_pk_mul_f32 v[52:53], v[54:55], v[58:59] op_sel_hi:[0,1]
	v_pk_mul_f32 v[46:47], v[46:47], v[52:53]
	v_pk_mul_f32 v[52:53], v[42:43], v[56:57] op_sel_hi:[1,0]
	v_pk_mul_f32 v[50:51], v[54:55], v[50:51] op_sel_hi:[0,1]
	v_exp_f32_e32 v52, v52
	v_exp_f32_e32 v53, v53
	v_pk_mul_f32 v[48:49], v[48:49], v[50:51]
	v_pk_mul_f32 v[50:51], v[44:45], v[56:57] op_sel_hi:[1,0]
; __device__ __forceinline__ unsigned pk2(float lo, float hi) { const f32x2 v = {lo, hi}; return __builtin_bit_cast(unsigned, __builtin_convertvector(v, bf16x2_t)); }
; #define PG8_BAR __builtin_amdgcn_s_barrier()
;     __device__ __forceinline__ void operator()(const f32x4 (&acc)[2][2][4][2], const Unit& u, int wr, int wc, int fr, int fq) const {
;     ...
;         for (int ai = 0; ai < 2; ++ai)
; #pragma unroll
;             for (int m = 0; m < 4; ++m) {
;                 const float rs = rs8[ai][m], nrs = -1.44269504089f * rs;
;                 u32x4 w;
; #pragma unroll
;                 for (int n = 0; n < 2; ++n) { const f32x4 gq = acc[ai][0][m][n], uq = acc[ai][1][m][n];
; #pragma unroll
;                     for (int h = 0; h < 2; ++h) { const f32x2 gv = (f32x2){gq[2 * h], gq[2 * h + 1]}, uv = (f32x2){uq[2 * h], uq[2 * h + 1]};
;                         const f32x2 ea = gv * nrs; f32x2 e; e.x = __builtin_amdgcn_exp2f(ea.x); e.y = __builtin_amdgcn_exp2f(ea.y);
;                         const f32x2 d = e + 1.0f; f32x2 rc; rc.x = __builtin_amdgcn_rcpf(d.x); rc.y = __builtin_amdgcn_rcpf(d.y);
;                         const f32x2 o = (gv * uv) * (rc * (rs * rs));
;                         w[2 * n + h] = pk2(o.x, o.y); } }
;                 *(u32x4*)(O + (size_t)(row0 + ai * HALF + m * 16) * ldc + col0) = w; }
; template <class Epi, class Sched>
; __device__ __forceinline__ void gemm_phase(LAS unsigned char* lds, const Gemm g, const Sched& S, const Epi& E) {
;     ...
;         if constexpr (!Epi::AFTER_DRAIN) { E(acc, cur, wr, wc, fr, fq); S.done(cur); }
;         if (!has_next) break;
; #pragma unroll
;         for (int a = 0; a < 2; ++a)
; #pragma unroll
;             for (int b = 0; b < 2; ++b)
; #pragma unroll
;                 for (int m = 0; m < 4; ++m)
; #pragma unroll
;                     for (int n = 0; n < 2; ++n) acc[a][b][m][n] = (f32x4){0.f, 0.f, 0.f, 0.f};
;         cur = nxt; cA = nA; cB = nB; ++ui;
;         if (wr == 1) PG8_BAR;
	v_cvt_pk_bf16_f32 v46, v46, v47
	v_exp_f32_e32 v50, v50
	v_exp_f32_e32 v51, v51
	v_cvt_pk_bf16_f32 v47, v48, v49
	v_pk_add_f32 v[48:49], v[52:53], 1.0 op_sel_hi:[1,0]
	v_pk_mul_f32 v[38:39], v[42:43], v[38:39]
	v_rcp_f32_e32 v48, v48
	v_rcp_f32_e32 v49, v49
	v_pk_add_f32 v[42:43], v[50:51], 1.0 op_sel_hi:[1,0]
	v_pk_mul_f32 v[40:41], v[44:45], v[40:41]
	v_rcp_f32_e32 v42, v42
	v_rcp_f32_e32 v43, v43
	v_pk_mul_f32 v[44:45], v[54:55], v[48:49] op_sel_hi:[0,1]
	v_pk_mul_f32 v[38:39], v[38:39], v[44:45]
	v_pk_mul_f32 v[30:31], v[34:35], v[30:31]
	v_cvt_pk_bf16_f32 v48, v38, v39
	v_pk_mul_f32 v[38:39], v[54:55], v[42:43] op_sel_hi:[0,1]
	v_pk_mul_f32 v[38:39], v[40:41], v[38:39]
	v_mul_f32_e32 v40, 0xbfb8aa3b, v145
	v_pk_mul_f32 v[42:43], v[34:35], v[40:41] op_sel_hi:[1,0]
	v_pk_mul_f32 v[34:35], v[36:37], v[40:41] op_sel_hi:[1,0]
	v_exp_f32_e32 v42, v42
	v_exp_f32_e32 v43, v43
	v_exp_f32_e32 v34, v34
	v_exp_f32_e32 v35, v35
	v_cvt_pk_bf16_f32 v49, v38, v39
	v_pk_add_f32 v[42:43], v[42:43], 1.0 op_sel_hi:[1,0]
	v_mad_u32_u24 v38, v146, s1, v120
	v_rcp_f32_e32 v42, v42
	v_rcp_f32_e32 v43, v43
	v_pk_add_f32 v[34:35], v[34:35], 1.0 op_sel_hi:[1,0]
	v_rcp_f32_e32 v34, v34
	v_rcp_f32_e32 v35, v35
	global_store_dwordx4 v38, v[46:49], s[12:13]
	v_mul_f32_e32 v38, v145, v145
	v_pk_mul_f32 v[32:33], v[36:37], v[32:33]
	v_pk_mul_f32 v[36:37], v[38:39], v[42:43] op_sel_hi:[0,1]
	v_pk_mul_f32 v[30:31], v[30:31], v[36:37]
	v_pk_mul_f32 v[36:37], v[26:27], v[40:41] op_sel_hi:[1,0]
	v_pk_mul_f32 v[34:35], v[38:39], v[34:35] op_sel_hi:[0,1]
	v_exp_f32_e32 v36, v36
	v_exp_f32_e32 v37, v37
	v_pk_mul_f32 v[32:33], v[32:33], v[34:35]
	v_pk_mul_f32 v[34:35], v[28:29], v[40:41] op_sel_hi:[1,0]
	v_cvt_pk_bf16_f32 v30, v30, v31
	v_exp_f32_e32 v34, v34
	v_exp_f32_e32 v35, v35
	v_cvt_pk_bf16_f32 v31, v32, v33
	v_pk_add_f32 v[32:33], v[36:37], 1.0 op_sel_hi:[1,0]
	v_pk_mul_f32 v[22:23], v[26:27], v[22:23]
	v_rcp_f32_e32 v32, v32
	v_rcp_f32_e32 v33, v33
	v_pk_add_f32 v[26:27], v[34:35], 1.0 op_sel_hi:[1,0]
	v_pk_mul_f32 v[24:25], v[28:29], v[24:25]
	v_rcp_f32_e32 v26, v26
	v_rcp_f32_e32 v27, v27
	v_pk_mul_f32 v[28:29], v[38:39], v[32:33] op_sel_hi:[0,1]
	v_pk_mul_f32 v[22:23], v[22:23], v[28:29]
	v_pk_mul_f32 v[14:15], v[18:19], v[14:15]
	v_cvt_pk_bf16_f32 v32, v22, v23
	v_pk_mul_f32 v[22:23], v[38:39], v[26:27] op_sel_hi:[0,1]
	v_pk_mul_f32 v[22:23], v[24:25], v[22:23]
	v_mul_f32_e32 v24, 0xbfb8aa3b, v143
	v_pk_mul_f32 v[26:27], v[18:19], v[24:25] op_sel_hi:[1,0]
	v_pk_mul_f32 v[18:19], v[20:21], v[24:25] op_sel_hi:[1,0]
	v_exp_f32_e32 v26, v26
	v_exp_f32_e32 v27, v27
	v_exp_f32_e32 v18, v18
	v_exp_f32_e32 v19, v19
	v_cvt_pk_bf16_f32 v33, v22, v23
	v_pk_add_f32 v[26:27], v[26:27], 1.0 op_sel_hi:[1,0]
	v_mad_u32_u24 v22, v144, s1, v120
	v_rcp_f32_e32 v26, v26
	v_rcp_f32_e32 v27, v27
	v_pk_add_f32 v[18:19], v[18:19], 1.0 op_sel_hi:[1,0]
	v_rcp_f32_e32 v18, v18
	v_rcp_f32_e32 v19, v19
	global_store_dwordx4 v22, v[30:33], s[12:13]
	v_mul_f32_e32 v22, v143, v143
	v_pk_mul_f32 v[16:17], v[20:21], v[16:17]
	v_pk_mul_f32 v[20:21], v[22:23], v[26:27] op_sel_hi:[0,1]
	v_pk_mul_f32 v[14:15], v[14:15], v[20:21]
	v_pk_mul_f32 v[20:21], v[10:11], v[24:25] op_sel_hi:[1,0]
	v_pk_mul_f32 v[18:19], v[22:23], v[18:19] op_sel_hi:[0,1]
	v_exp_f32_e32 v20, v20
	v_exp_f32_e32 v21, v21
	v_pk_mul_f32 v[16:17], v[16:17], v[18:19]
	v_pk_mul_f32 v[18:19], v[12:13], v[24:25] op_sel_hi:[1,0]
	v_cvt_pk_bf16_f32 v14, v14, v15
	v_exp_f32_e32 v18, v18
	v_exp_f32_e32 v19, v19
	v_cvt_pk_bf16_f32 v15, v16, v17
	v_pk_add_f32 v[16:17], v[20:21], 1.0 op_sel_hi:[1,0]
	v_pk_mul_f32 v[6:7], v[10:11], v[6:7]
	v_rcp_f32_e32 v16, v16
	v_rcp_f32_e32 v17, v17
	v_pk_add_f32 v[10:11], v[18:19], 1.0 op_sel_hi:[1,0]
	v_pk_mul_f32 v[8:9], v[12:13], v[8:9]
	v_rcp_f32_e32 v10, v10
	v_rcp_f32_e32 v11, v11
	v_pk_mul_f32 v[12:13], v[22:23], v[16:17] op_sel_hi:[0,1]
	v_pk_mul_f32 v[6:7], v[6:7], v[12:13]
	s_andn2_b64 vcc, exec, s[38:39]
	v_cvt_pk_bf16_f32 v16, v6, v7
	v_pk_mul_f32 v[6:7], v[22:23], v[10:11] op_sel_hi:[0,1]
	v_pk_mul_f32 v[6:7], v[8:9], v[6:7]
	s_nop 0
	v_cvt_pk_bf16_f32 v17, v6, v7
	v_mad_u32_u24 v6, v142, s1, v120
	s_mov_b64 s[26:27], -1
	global_store_dwordx4 v6, v[14:17], s[12:13]
	s_cbranch_vccnz .LBB0_133
	s_andn2_b64 vcc, exec, s[10:11]
	s_cbranch_vccnz .LBB0_132
	s_barrier
	s_branch .LBB0_132

; #define PG8_STAGE(bufoff, gbase, voff) do { _Pragma("unroll") for (int _i = 0; _i < 2; ++_i) \
;         __builtin_amdgcn_global_load_lds((const unsigned*)((const char*)(gbase) + (voff)[_i]), (LAS unsigned*)(lds + (bufoff) + ldsw + _i * 8192), 16, 0, 0); } while (0)
; #define PG8_WAIT_V(n) asm volatile("s_waitcnt vmcnt(" #n ")" ::: "memory")
; #define PG8_BAR __builtin_amdgcn_s_barrier()
; template <class Epi, class Sched>
; __device__ __forceinline__ void gemm_phase(LAS unsigned char* lds, const Gemm g, const Sched& S, const Epi& E) {
;     ...
;     f32x4 acc[2][2][4][2];
; #pragma unroll
;     for (int a = 0; a < 2; ++a)
; #pragma unroll
;         for (int b = 0; b < 2; ++b)
; #pragma unroll
;             for (int m = 0; m < 4; ++m)
; #pragma unroll
;                 for (int n = 0; n < 2; ++n) acc[a][b][m][n] = (f32x4){0.f, 0.f, 0.f, 0.f};
;     bf16x8 At[4][2], B0[2][2], B1[2][2];
;     const char* cA = (const char*)g.A + (size_t)cur.pm * tstepA + (size_t)cur.ka * 2; const char* cB = (const char*)g.Bt + (size_t)cur.pn * tstepB;
;     S.a_ready(cur);
;     PG8_STAGE(PG8_SB(0, 0), cB, voffB); PG8_STAGE(PG8_SB(0, 1), cB + hstepB, voffB); PG8_STAGE(PG8_SA(0, 0), cA, voffA); PG8_STAGE(PG8_SA(0, 1), cA + hstepA, voffA);
;     if (wr == 1) PG8_BAR;
;     PG8_WAIT_V(2); PG8_BAR;
;     PG8_STAGE(PG8_SB(1, 0), cB + kstep, voffB); PG8_STAGE(PG8_SA(1, 0), cA + kstep, voffA); PG8_STAGE(PG8_SB(1, 1), cB + hstepB + kstep, voffB);
;     PG8_WAIT_V(6); PG8_BAR;
.LBB0_267:
	v_lshl_add_u64 v[14:15], s[24:25], 0, v[4:5]
	v_mov_b32_e32 v3, v5
	v_and_b32_e32 v142, 15, v143
	v_and_b32_e32 v22, 48, v143
	v_lshlrev_b32_e32 v23, 2, v143
	v_lshl_add_u64 v[16:17], s[24:25], 0, v[2:3]
	s_and_b32 s48, s44, 3
	v_lshl_or_b32 v22, v142, 6, v22
	s_lshl_b32 s4, s47, 13
	v_and_b32_e32 v23, 32, v23
	s_add_i32 m0, s50, 0x18000
	v_lshl_add_u64 v[14:15], v[14:15], 0, s[36:37]
	v_lshl_add_u64 v[18:19], s[20:21], 0, v[4:5]
	v_bitop3_b32 v24, v22, s4, v23 bitop3:0xde
	s_lshl_b32 s4, s48, 12
	s_waitcnt vmcnt(2)
	s_barrier
	global_load_lds_dwordx4 v[14:15], off
	v_lshl_add_u64 v[14:15], v[16:17], 0, s[36:37]
	s_add_i32 m0, s50, 0x1a000
	s_add_i32 s54, s50, 0x8000
	s_add_i32 s55, s50, 0xa000
	v_lshl_add_u64 v[20:21], s[20:21], 0, v[2:3]
	v_bitop3_b32 v144, v22, s4, v23 bitop3:0xde
	global_load_lds_dwordx4 v[14:15], off
	v_lshl_add_u64 v[14:15], v[18:19], 0, s[36:37]
	s_mov_b32 m0, s54
	s_add_u32 s4, s24, 0x158080
	global_load_lds_dwordx4 v[14:15], off
	v_lshl_add_u64 v[14:15], v[20:21], 0, s[36:37]
	s_mov_b32 m0, s55
	s_addc_u32 s5, s25, 0
	global_load_lds_dwordx4 v[14:15], off
	s_add_i32 m0, s50, 0x1c000
	v_lshl_add_u64 v[14:15], s[4:5], 0, v[4:5]
	global_load_lds_dwordx4 v[14:15], off
	v_lshl_add_u64 v[14:15], s[4:5], 0, v[2:3]
	s_add_i32 m0, s50, 0x1e000
	s_movk_i32 s10, 0x1580
	global_load_lds_dwordx4 v[14:15], off
	v_lshrrev_b32_e32 v11, 1, v11
	v_mul_lo_u32 v10, v10, s10
	s_mov_b32 s22, 0x15800
	v_mad_u64_u32 v[10:11], s[4:5], v11, s22, v[10:11]
	v_or_b32_e32 v10, v10, v12
	v_add_lshl_u32 v134, v10, v13, 1
	v_lshrrev_b32_e32 v10, 1, v6
	v_mul_lo_u32 v6, v7, s10
	v_mad_u64_u32 v[6:7], s[4:5], v10, s22, v[6:7]
	s_waitcnt vmcnt(6)
	v_or_b32_e32 v6, v6, v8
	s_cmpk_lt_u32 s45, 0x100
	v_add_lshl_u32 v136, v6, v9, 1
	v_mov_b32_e32 v6, 0
	v_readlane_b32 s4, v254, 13
	s_cselect_b64 s[18:19], -1, 0
	v_mov_b32_e32 v135, v5
	v_mov_b32_e32 v137, v5
	s_mov_b32 s59, 0
	v_add_u32_e32 v145, 0, v24
	s_mov_b32 s10, s4
	v_readlane_b32 s46, v253, 61
	v_mov_b32_e32 v7, v6
	v_mov_b32_e32 v8, v6
	v_mov_b32_e32 v9, v6
	v_mov_b32_e32 v10, v6
	v_mov_b32_e32 v11, v6
	v_mov_b32_e32 v12, v6
	v_mov_b32_e32 v13, v6
	v_mov_b32_e32 v14, v6
	v_mov_b32_e32 v15, v6
	v_mov_b32_e32 v16, v6
	v_mov_b32_e32 v17, v6
	v_mov_b32_e32 v18, v6
	v_mov_b32_e32 v19, v6
	v_mov_b32_e32 v20, v6
	v_mov_b32_e32 v21, v6
	v_mov_b32_e32 v22, v6
	v_mov_b32_e32 v23, v6
	v_mov_b32_e32 v24, v6
	v_mov_b32_e32 v25, v6
	v_mov_b32_e32 v30, v6
	v_mov_b32_e32 v31, v6
	v_mov_b32_e32 v32, v6
	v_mov_b32_e32 v33, v6
	v_mov_b32_e32 v38, v6
	v_mov_b32_e32 v39, v6
	v_mov_b32_e32 v40, v6
	v_mov_b32_e32 v41, v6
	v_mov_b32_e32 v46, v6
	v_mov_b32_e32 v47, v6
	v_mov_b32_e32 v48, v6
	v_mov_b32_e32 v49, v6
	v_mov_b32_e32 v26, v6
	v_mov_b32_e32 v27, v6
	v_mov_b32_e32 v28, v6
	v_mov_b32_e32 v29, v6
	v_mov_b32_e32 v34, v6
	v_mov_b32_e32 v35, v6
	v_mov_b32_e32 v36, v6
	v_mov_b32_e32 v37, v6
	v_mov_b32_e32 v42, v6
	v_mov_b32_e32 v43, v6
	v_mov_b32_e32 v44, v6
	v_mov_b32_e32 v45, v6
	v_mov_b32_e32 v50, v6
	v_mov_b32_e32 v51, v6
	v_mov_b32_e32 v52, v6
	v_mov_b32_e32 v53, v6
	v_mov_b32_e32 v54, v6
	v_mov_b32_e32 v55, v6
	v_mov_b32_e32 v56, v6
	v_mov_b32_e32 v57, v6
	v_mov_b32_e32 v58, v6
	v_mov_b32_e32 v59, v6
	v_mov_b32_e32 v60, v6
	v_mov_b32_e32 v61, v6
	v_mov_b32_e32 v62, v6
	v_mov_b32_e32 v63, v6
	v_mov_b32_e32 v64, v6
	v_mov_b32_e32 v65, v6
	v_mov_b32_e32 v66, v6
	v_mov_b32_e32 v67, v6
	v_mov_b32_e32 v68, v6
	v_mov_b32_e32 v69, v6
	v_mov_b32_e32 v70, v6
	v_mov_b32_e32 v71, v6
	v_mov_b32_e32 v72, v6
	v_mov_b32_e32 v73, v6
	v_mov_b32_e32 v74, v6
	v_mov_b32_e32 v75, v6
	v_mov_b32_e32 v76, v6
	v_mov_b32_e32 v77, v6
	v_mov_b32_e32 v78, v6
	v_mov_b32_e32 v79, v6
	v_mov_b32_e32 v80, v6
	v_mov_b32_e32 v81, v6
	v_mov_b32_e32 v82, v6
	v_mov_b32_e32 v83, v6
	v_mov_b32_e32 v84, v6
	v_mov_b32_e32 v85, v6
	v_mov_b32_e32 v86, v6
	v_mov_b32_e32 v87, v6
	v_mov_b32_e32 v88, v6
	v_mov_b32_e32 v89, v6
	v_mov_b32_e32 v94, v6
	v_mov_b32_e32 v95, v6
	v_mov_b32_e32 v96, v6
	v_mov_b32_e32 v97, v6
	v_mov_b32_e32 v102, v6
	v_mov_b32_e32 v103, v6
	v_mov_b32_e32 v104, v6
	v_mov_b32_e32 v105, v6
	v_mov_b32_e32 v114, v6
	v_mov_b32_e32 v115, v6
	v_mov_b32_e32 v116, v6
	v_mov_b32_e32 v117, v6
	v_mov_b32_e32 v90, v6
	v_mov_b32_e32 v91, v6
	v_mov_b32_e32 v92, v6
	v_mov_b32_e32 v93, v6
	v_mov_b32_e32 v98, v6
	v_mov_b32_e32 v99, v6
	v_mov_b32_e32 v100, v6
	v_mov_b32_e32 v101, v6
	v_mov_b32_e32 v106, v6
	v_mov_b32_e32 v107, v6
	v_mov_b32_e32 v108, v6
	v_mov_b32_e32 v109, v6
	v_mov_b32_e32 v110, v6
	v_mov_b32_e32 v111, v6
	v_mov_b32_e32 v112, v6
	v_mov_b32_e32 v113, v6
	v_mov_b32_e32 v118, v6
	v_mov_b32_e32 v119, v6
	v_mov_b32_e32 v120, v6
	v_mov_b32_e32 v121, v6
	v_mov_b32_e32 v122, v6
	v_mov_b32_e32 v123, v6
	v_mov_b32_e32 v124, v6
	v_mov_b32_e32 v125, v6
	v_mov_b32_e32 v126, v6
	v_mov_b32_e32 v127, v6
	v_mov_b32_e32 v128, v6
	v_mov_b32_e32 v129, v6
	v_mov_b32_e32 v130, v6
	v_mov_b32_e32 v131, v6
	v_mov_b32_e32 v132, v6
	v_mov_b32_e32 v133, v6
	s_barrier
	s_branch .LBB0_270
	s_nop 0
	s_nop 0
	s_nop 0
	s_nop 0
	s_nop 0
	s_nop 0
	s_nop 0
.LBB0_268:
	s_mov_b64 s[22:23], s[24:25]
	s_mov_b64 s[4:5], s[20:21]
	s_mov_b32 s58, s59
	s_andn2_b64 vcc, exec, s[38:39]
	s_cbranch_vccz .LBB0_288
